# P1 modulated-norm row loop: modulation loads of each four-piece group issued ahead of the previous group's stores (cloned address chains), on top of epilogue load batching
# baseline (speedup 1.0000x reference)
.LBB0_269:
	v_lshl_add_u64 v[2:3], s[18:19], 0, v[66:67]
	global_load_dwordx4 v[38:41], v66, s[18:19]
	global_load_dwordx4 v[58:61], v66, s[18:19] offset:1024
	global_load_dwordx4 v[62:65], v66, s[18:19] offset:2048
	global_load_dwordx4 v[54:57], v66, s[18:19] offset:3072
	v_add_co_u32_e32 v6, vcc, s26, v2
	s_lshr_b32 s8, s8, 10
	s_nop 0
	v_addc_co_u32_e32 v7, vcc, 0, v3, vcc
	global_load_dwordx4 v[42:45], v[6:7], off offset:-4096
	v_add_co_u32_e32 v4, vcc, s27, v2
	s_add_i32 s8, s8, 1
	s_nop 0
	v_addc_co_u32_e32 v5, vcc, 0, v3, vcc
	global_load_dwordx4 v[34:37], v[4:5], off offset:3072
	global_load_dwordx4 v[50:53], v[4:5], off offset:1024
	global_load_dwordx4 v[46:49], v[4:5], off offset:2048
	global_load_dwordx4 v[22:25], v[6:7], off offset:1024
	s_waitcnt lgkmcnt(3)
	global_load_dwordx4 v[26:29], v[6:7], off
	global_load_dwordx4 v[18:21], v[6:7], off offset:2048
	v_add_co_u32_e32 v14, vcc, s28, v2
	s_and_b64 s[2:3], s[2:3], exec
	s_nop 0
	v_addc_co_u32_e32 v15, vcc, 0, v3, vcc
	global_load_dwordx4 v[2:5], v[14:15], off
	s_waitcnt lgkmcnt(0)
	global_load_dwordx4 v[30:33], v[6:7], off offset:3072
	s_nop 0
	global_load_dwordx4 v[6:9], v[14:15], off offset:1024
	global_load_dwordx4 v[10:13], v[14:15], off offset:2048
	s_nop 0
	global_load_dwordx4 v[14:17], v[14:15], off offset:3072
	s_cselect_b32 s2, 0, s8
	s_mul_hi_u32 s3, s2, 0x18000
	s_mul_i32 s2, s2, 0x18000
	v_readlane_b32 s18, v237, 57
	v_readlane_b32 s19, v237, 58
	s_add_u32 s18, s18, s2
	s_addc_u32 s19, s19, s3
	s_add_u32 s20, s18, 0x4000
	s_addc_u32 s21, s19, 0
	global_load_dwordx4 v[188:191], v[70:71], off
	v_lshlrev_b32_e32 v114, 2, v68
	global_load_dwordx4 v[194:197], v114, s[20:21]
	v_lshlrev_b32_e32 v114, 2, v68
	global_load_dwordx4 v[202:205], v114, s[18:19]
	global_load_dwordx4 v[206:209], v[70:71], off offset:1024
	global_load_dwordx4 v[212:215], v105, s[20:21]
	v_lshlrev_b32_e32 v114, 2, v68
	global_load_dwordx4 v[220:223], v114, s[18:19] offset:1024
	global_load_dwordx4 v[224:227], v[70:71], off offset:2048
	global_load_dwordx4 v[228:231], v109, s[20:21]
	v_lshlrev_b32_e32 v114, 2, v68
	global_load_dwordx4 v[238:241], v114, s[18:19] offset:2048
	global_load_dwordx4 v[242:245], v[70:71], off offset:3072
	global_load_dwordx4 v[246:249], v121, s[20:21]
	v_lshlrev_b32_e32 v114, 2, v68
	global_load_dwordx4 v[250:253], v114, s[18:19] offset:3072
	s_waitcnt vmcnt(0)
	v_pk_mul_f32 v[114:115], v[40:41], v[40:41]
	v_pk_mul_f32 v[116:117], v[38:39], v[38:39]
	v_pk_mul_f32 v[118:119], v[60:61], v[60:61]
	v_pk_mul_f32 v[128:129], v[58:59], v[58:59]
	v_pk_mov_b32 v[132:133], v[116:117], v[114:115] op_sel:[1,0]
	v_mov_b32_e32 v117, v115
	v_pk_mov_b32 v[114:115], v[128:129], v[118:119] op_sel:[1,0]
	v_mov_b32_e32 v129, v119
	v_mul_f32_e32 v120, v63, v63
	v_mul_f32_e32 v130, v65, v65
	v_pk_add_f32 v[116:117], v[132:133], v[116:117]
	v_pk_add_f32 v[114:115], v[114:115], v[128:129]
	v_mul_f32_e32 v127, v56, v56
	v_mul_f32_e32 v134, v57, v57
	v_mul_f32_e32 v142, v54, v54
	v_mul_f32_e32 v143, v55, v55
	v_pk_fma_f32 v[118:119], v[62:63], v[62:63], v[120:121] op_sel_hi:[1,1,0]
	v_pk_fma_f32 v[130:131], v[64:65], v[64:65], v[130:131] op_sel_hi:[1,1,0]
	v_pk_add_f32 v[116:117], v[116:117], v[116:117] op_sel:[0,1] op_sel_hi:[1,0]
	v_pk_add_f32 v[114:115], v[114:115], v[114:115] op_sel:[0,1] op_sel_hi:[1,0]
	v_mov_b32_e32 v119, v127
	v_mov_b32_e32 v131, v134
	v_pk_mul_f32 v[128:129], v[44:45], v[44:45]
	v_pk_mul_f32 v[132:133], v[42:43], v[42:43]
	v_mov_b32_e32 v117, v142
	v_mov_b32_e32 v115, v143
	v_pk_add_f32 v[118:119], v[118:119], v[130:131]
	v_pk_mov_b32 v[130:131], v[132:133], v[128:129] op_sel:[1,0]
	v_mov_b32_e32 v133, v129
	v_pk_add_f32 v[114:115], v[116:117], v[114:115]
	v_pk_mul_f32 v[134:135], v[36:37], v[36:37]
	v_pk_mul_f32 v[136:137], v[34:35], v[34:35]
	v_mul_f32_e32 v120, v51, v51
	v_mul_f32_e32 v138, v53, v53
	v_pk_add_f32 v[130:131], v[130:131], v[132:133]
	v_pk_add_f32 v[114:115], v[114:115], v[118:119]
	v_mul_f32_e32 v127, v48, v48
	v_mul_f32_e32 v144, v49, v49
	v_mul_f32_e32 v145, v47, v47
	v_mul_f32_e32 v146, v46, v46
	v_pk_mov_b32 v[128:129], v[136:137], v[134:135] op_sel:[1,0]
	v_mov_b32_e32 v137, v135
	v_pk_fma_f32 v[134:135], v[50:51], v[50:51], v[120:121] op_sel_hi:[1,1,0]
	v_pk_fma_f32 v[138:139], v[52:53], v[52:53], v[138:139] op_sel_hi:[1,1,0]
	v_pk_add_f32 v[130:131], v[130:131], v[130:131] op_sel:[0,1] op_sel_hi:[1,0]
	v_pk_add_f32 v[114:115], v[114:115], v[114:115] op_sel:[0,1] op_sel_hi:[1,0]
	v_mov_b32_e32 v135, v127
	v_mov_b32_e32 v139, v144
	v_mov_b32_e32 v131, v145
	v_mov_b32_e32 v115, v146
	v_pk_add_f32 v[116:117], v[134:135], v[138:139]
	v_pk_add_f32 v[114:115], v[114:115], v[130:131]
	v_mul_f32_e32 v140, v27, v27
	v_pk_add_f32 v[128:129], v[128:129], v[136:137]
	v_pk_add_f32 v[114:115], v[114:115], v[116:117]
	v_mul_f32_e32 v116, v29, v29
	v_mul_f32_e32 v147, v23, v23
	v_mul_f32_e32 v148, v22, v22
	v_mul_f32_e32 v149, v24, v24
	v_pk_fma_f32 v[140:141], v[26:27], v[26:27], v[140:141] op_sel_hi:[1,1,0]
	v_pk_add_f32 v[128:129], v[128:129], v[128:129] op_sel:[0,1] op_sel_hi:[1,0]
	v_pk_add_f32 v[114:115], v[114:115], v[114:115] op_sel:[0,1] op_sel_hi:[1,0]
	v_pk_fma_f32 v[116:117], v[28:29], v[28:29], v[116:117] op_sel_hi:[1,1,0]
	v_mov_b32_e32 v141, v149
	v_mov_b32_e32 v129, v147
	v_mov_b32_e32 v115, v148
	v_mul_f32_e32 v117, v25, v25
	v_pk_add_f32 v[114:115], v[114:115], v[128:129]
	v_pk_add_f32 v[116:117], v[140:141], v[116:117]
	v_pk_mul_f32 v[118:119], v[18:19], v[18:19]
	v_pk_add_f32 v[114:115], v[114:115], v[116:117]
	v_pk_mul_f32 v[116:117], v[20:21], v[20:21]
	v_pk_add_f32 v[114:115], v[114:115], v[114:115] op_sel:[0,1] op_sel_hi:[1,0]
	v_pk_mov_b32 v[128:129], v[118:119], v[116:117] op_sel:[1,0]
	v_mov_b32_e32 v119, v117
	v_pk_add_f32 v[116:117], v[128:129], v[118:119]
	v_mul_f32_e32 v115, v2, v2
	v_pk_add_f32 v[116:117], v[116:117], v[116:117] op_sel:[0,1] op_sel_hi:[1,0]
	v_mul_f32_e32 v118, v33, v33
	v_mul_f32_e32 v117, v3, v3
	v_pk_add_f32 v[114:115], v[114:115], v[116:117]
	v_mul_f32_e32 v116, v31, v31
	v_pk_fma_f32 v[116:117], v[30:31], v[30:31], v[116:117] op_sel_hi:[1,1,0]
	v_pk_fma_f32 v[118:119], v[32:33], v[32:33], v[118:119] op_sel_hi:[1,1,0]
	v_mul_f32_e32 v117, v4, v4
	v_mul_f32_e32 v119, v5, v5
	v_pk_add_f32 v[116:117], v[116:117], v[118:119]
	v_pk_mul_f32 v[118:119], v[6:7], v[6:7]
	v_pk_add_f32 v[114:115], v[114:115], v[116:117]
	v_pk_mul_f32 v[116:117], v[8:9], v[8:9]
	v_pk_add_f32 v[114:115], v[114:115], v[114:115] op_sel:[0,1] op_sel_hi:[1,0]
	v_pk_mov_b32 v[128:129], v[118:119], v[116:117] op_sel:[1,0]
	v_mov_b32_e32 v119, v117
	v_pk_add_f32 v[116:117], v[128:129], v[118:119]
	v_mul_f32_e32 v115, v14, v14
	v_pk_add_f32 v[116:117], v[116:117], v[116:117] op_sel:[0,1] op_sel_hi:[1,0]
	v_mul_f32_e32 v118, v13, v13
	v_mul_f32_e32 v117, v15, v15
	v_pk_add_f32 v[114:115], v[114:115], v[116:117]
	v_mul_f32_e32 v116, v11, v11
	v_pk_fma_f32 v[116:117], v[10:11], v[10:11], v[116:117] op_sel_hi:[1,1,0]
	v_pk_fma_f32 v[118:119], v[12:13], v[12:13], v[118:119] op_sel_hi:[1,1,0]
	v_mul_f32_e32 v117, v16, v16
	v_mul_f32_e32 v119, v17, v17
	v_pk_add_f32 v[116:117], v[116:117], v[118:119]
	v_lshlrev_b32_e32 v120, 2, v68
	v_pk_add_f32 v[114:115], v[114:115], v[116:117]
	s_nop 0
	v_add_f32_e32 v118, v114, v115
	ds_bpermute_b32 v119, v1, v118
	s_waitcnt lgkmcnt(0)
	v_add_f32_e32 v118, v118, v119
	ds_bpermute_b32 v119, v81, v118
	s_waitcnt lgkmcnt(0)
	v_add_f32_e32 v118, v118, v119
	ds_bpermute_b32 v119, v85, v118
	s_waitcnt lgkmcnt(0)
	v_add_f32_e32 v118, v118, v119
	ds_bpermute_b32 v119, v89, v118
	s_waitcnt lgkmcnt(0)
	v_add_f32_e32 v118, v118, v119
	ds_bpermute_b32 v119, v93, v118
	s_waitcnt lgkmcnt(0)
	v_add_f32_e32 v118, v118, v119
	ds_bpermute_b32 v119, v97, v118
	s_waitcnt lgkmcnt(0)
	v_add_f32_e32 v118, v118, v119
	v_fmamk_f32 v118, v118, 0x39800000, v69
	v_mul_f32_e32 v119, 0x4f800000, v118
	v_cmp_gt_f32_e32 vcc, s29, v118
	s_nop 1
	v_cndmask_b32_e32 v118, v118, v119, vcc
	v_sqrt_f32_e32 v119, v118
	s_nop 0
	v_add_u32_e32 v120, -1, v119
	v_fma_f32 v127, -v120, v119, v118
	v_cmp_ge_f32_e64 s[2:3], 0, v127
	v_add_u32_e32 v127, 1, v119
	s_nop 0
	v_cndmask_b32_e64 v120, v119, v120, s[2:3]
	v_fma_f32 v119, -v127, v119, v118
	v_cmp_lt_f32_e64 s[2:3], 0, v119
	s_nop 1
	v_cndmask_b32_e64 v119, v120, v127, s[2:3]
	v_mul_f32_e32 v120, 0x37800000, v119
	v_cndmask_b32_e32 v119, v119, v120, vcc
	v_cmp_class_f32_e32 vcc, v118, v101
	s_nop 1
	v_cndmask_b32_e32 v118, v119, v118, vcc
	v_div_scale_f32 v119, s[2:3], v118, v118, 1.0
	v_rcp_f32_e32 v120, v119
	s_lshl_b64 s[2:3], s[16:17], 13
	s_add_u32 s2, s22, s2
	s_addc_u32 s3, s23, s3
	v_fma_f32 v127, -v119, v120, 1.0
	v_fmac_f32_e32 v120, v127, v120
	v_div_scale_f32 v127, vcc, 1.0, v118, 1.0
	v_mul_f32_e32 v169, v127, v120
	v_fma_f32 v174, -v119, v169, v127
	v_fmac_f32_e32 v169, v174, v120
	v_fma_f32 v119, -v119, v169, v127
	v_div_fmas_f32 v119, v119, v120, v169
	v_div_fixup_f32 v120, v119, v118, 1.0
	v_pk_mul_f32 v[40:41], v[40:41], v[120:121] op_sel_hi:[1,0]
	v_pk_mul_f32 v[38:39], v[38:39], v[120:121] op_sel_hi:[1,0]
	v_pk_mul_f32 v[40:41], v[190:191], v[40:41]
	v_pk_mul_f32 v[38:39], v[188:189], v[38:39]
	v_pk_add_f32 v[114:115], v[196:197], 1.0 op_sel_hi:[1,0]
	v_pk_add_f32 v[118:119], v[194:195], 1.0 op_sel_hi:[1,0]
	v_pk_fma_f32 v[116:117], v[114:115], v[40:41], v[204:205]
	v_pk_fma_f32 v[118:119], v[118:119], v[38:39], v[202:203]
	v_pk_mul_f32 v[38:39], v[60:61], v[120:121] op_sel_hi:[1,0]
	v_pk_mul_f32 v[40:41], v[58:59], v[120:121] op_sel_hi:[1,0]
	v_pk_mul_f32 v[38:39], v[208:209], v[38:39]
	v_pk_mul_f32 v[40:41], v[206:207], v[40:41]
	v_pk_add_f32 v[58:59], v[214:215], 1.0 op_sel_hi:[1,0]
	v_pk_add_f32 v[114:115], v[212:213], 1.0 op_sel_hi:[1,0]
	v_pk_fma_f32 v[60:61], v[58:59], v[38:39], v[222:223]
	v_pk_fma_f32 v[114:115], v[114:115], v[40:41], v[220:221]
	v_pk_mul_f32 v[38:39], v[64:65], v[120:121] op_sel_hi:[1,0]
	v_pk_mul_f32 v[40:41], v[62:63], v[120:121] op_sel_hi:[1,0]
	v_pk_mul_f32 v[38:39], v[226:227], v[38:39]
	v_pk_mul_f32 v[58:59], v[224:225], v[40:41]
	v_pk_add_f32 v[40:41], v[230:231], 1.0 op_sel_hi:[1,0]
	v_pk_add_f32 v[62:63], v[228:229], 1.0 op_sel_hi:[1,0]
	v_pk_fma_f32 v[40:41], v[40:41], v[38:39], v[240:241]
	v_pk_mul_f32 v[38:39], v[56:57], v[120:121] op_sel_hi:[1,0]
	v_pk_add_f32 v[56:57], v[248:249], 1.0 op_sel_hi:[1,0]
	v_pk_mul_f32 v[38:39], v[244:245], v[38:39]
	v_pk_mul_f32 v[54:55], v[54:55], v[120:121] op_sel_hi:[1,0]
	v_pk_fma_f32 v[38:39], v[56:57], v[38:39], v[252:253]
	v_cvt_pk_bf16_f32 v56, v118, v119
	v_cvt_pk_bf16_f32 v57, v116, v117
	v_lshlrev_b32_e32 v127, 1, v68
	v_pk_fma_f32 v[58:59], v[62:63], v[58:59], v[238:239]
	v_pk_mul_f32 v[54:55], v[242:243], v[54:55]
	v_pk_add_f32 v[62:63], v[246:247], 1.0 op_sel_hi:[1,0]
	global_store_dwordx2 v127, v[56:57], s[2:3]
	v_cvt_pk_bf16_f32 v56, v114, v115
	v_cvt_pk_bf16_f32 v57, v60, v61
	v_pk_fma_f32 v[54:55], v[62:63], v[54:55], v[250:251]
	global_load_dwordx4 v[188:191], v[72:73], off
	global_load_dwordx4 v[194:197], v122, s[20:21]
	global_load_dwordx4 v[202:205], v122, s[18:19]
	global_load_dwordx4 v[206:209], v[74:75], off
	global_load_dwordx4 v[212:215], v123, s[20:21]
	global_load_dwordx4 v[220:223], v123, s[18:19]
	global_load_dwordx4 v[224:227], v[76:77], off
	global_load_dwordx4 v[228:231], v124, s[20:21]
	global_load_dwordx4 v[238:241], v124, s[18:19]
	global_load_dwordx4 v[242:245], v[78:79], off
	global_load_dwordx4 v[246:249], v125, s[20:21]
	global_load_dwordx4 v[250:253], v125, s[18:19]
	global_store_dwordx2 v127, v[56:57], s[2:3] offset:512
	v_cvt_pk_bf16_f32 v56, v58, v59
	v_cvt_pk_bf16_f32 v57, v40, v41
	global_store_dwordx2 v127, v[56:57], s[2:3] offset:1024
	v_cvt_pk_bf16_f32 v56, v54, v55
	v_cvt_pk_bf16_f32 v57, v38, v39
	global_store_dwordx2 v127, v[56:57], s[2:3] offset:1536
	v_pk_mul_f32 v[44:45], v[44:45], v[120:121] op_sel_hi:[1,0]
	v_pk_mul_f32 v[42:43], v[42:43], v[120:121] op_sel_hi:[1,0]
	v_pk_mul_f32 v[36:37], v[36:37], v[120:121] op_sel_hi:[1,0]
	v_pk_mul_f32 v[34:35], v[34:35], v[120:121] op_sel_hi:[1,0]
	v_pk_mul_f32 v[28:29], v[28:29], v[120:121] op_sel_hi:[1,0]
	v_pk_mul_f32 v[26:27], v[26:27], v[120:121] op_sel_hi:[1,0]
	v_pk_mul_f32 v[24:25], v[24:25], v[120:121] op_sel_hi:[1,0]
	v_pk_mul_f32 v[22:23], v[22:23], v[120:121] op_sel_hi:[1,0]
	v_pk_mul_f32 v[20:21], v[20:21], v[120:121] op_sel_hi:[1,0]
	v_pk_mul_f32 v[18:19], v[18:19], v[120:121] op_sel_hi:[1,0]
	v_pk_mul_f32 v[4:5], v[4:5], v[120:121] op_sel_hi:[1,0]
	v_pk_mul_f32 v[2:3], v[2:3], v[120:121] op_sel_hi:[1,0]
	v_pk_mul_f32 v[14:15], v[14:15], v[120:121] op_sel_hi:[1,0]
	v_pk_mul_f32 v[8:9], v[8:9], v[120:121] op_sel_hi:[1,0]
	v_pk_mul_f32 v[10:11], v[10:11], v[120:121] op_sel_hi:[1,0]
	v_pk_mul_f32 v[6:7], v[6:7], v[120:121] op_sel_hi:[1,0]
	v_pk_mul_f32 v[12:13], v[12:13], v[120:121] op_sel_hi:[1,0]
	s_waitcnt vmcnt(0)
	v_pk_mul_f32 v[42:43], v[42:43], v[188:189]
	v_pk_mul_f32 v[44:45], v[44:45], v[190:191]
	v_pk_add_f32 v[56:57], v[196:197], 1.0 op_sel_hi:[1,0]
	v_pk_add_f32 v[62:63], v[194:195], 1.0 op_sel_hi:[1,0]
	v_pk_fma_f32 v[56:57], v[44:45], v[56:57], v[204:205]
	v_pk_fma_f32 v[62:63], v[42:43], v[62:63], v[202:203]
	v_pk_mul_f32 v[42:43], v[52:53], v[120:121] op_sel_hi:[1,0]
	v_pk_mul_f32 v[44:45], v[50:51], v[120:121] op_sel_hi:[1,0]
	v_pk_mul_f32 v[42:43], v[42:43], v[208:209]
	v_pk_mul_f32 v[44:45], v[44:45], v[206:207]
	v_pk_add_f32 v[50:51], v[214:215], 1.0 op_sel_hi:[1,0]
	v_pk_add_f32 v[52:53], v[212:213], 1.0 op_sel_hi:[1,0]
	v_pk_fma_f32 v[50:51], v[42:43], v[50:51], v[222:223]
	v_pk_fma_f32 v[52:53], v[44:45], v[52:53], v[220:221]
	v_pk_mul_f32 v[42:43], v[48:49], v[120:121] op_sel_hi:[1,0]
	v_pk_mul_f32 v[44:45], v[46:47], v[120:121] op_sel_hi:[1,0]
	v_pk_mul_f32 v[42:43], v[42:43], v[226:227]
	v_pk_mul_f32 v[44:45], v[44:45], v[224:225]
	v_pk_add_f32 v[46:47], v[230:231], 1.0 op_sel_hi:[1,0]
	v_pk_add_f32 v[48:49], v[228:229], 1.0 op_sel_hi:[1,0]
	v_pk_fma_f32 v[42:43], v[42:43], v[46:47], v[240:241]
	v_pk_fma_f32 v[44:45], v[44:45], v[48:49], v[238:239]
	v_pk_mul_f32 v[46:47], v[34:35], v[242:243]
	v_pk_mul_f32 v[34:35], v[36:37], v[244:245]
	v_pk_add_f32 v[36:37], v[248:249], 1.0 op_sel_hi:[1,0]
	v_pk_add_f32 v[48:49], v[246:247], 1.0 op_sel_hi:[1,0]
	v_pk_fma_f32 v[34:35], v[34:35], v[36:37], v[252:253]
	v_pk_fma_f32 v[36:37], v[46:47], v[48:49], v[250:251]
	global_load_dwordx4 v[188:191], v[82:83], off
	v_lshlrev_b32_e32 v46, 2, v80
	global_load_dwordx4 v[194:197], v46, s[20:21]
	v_lshlrev_b32_e32 v46, 2, v80
	global_load_dwordx4 v[202:205], v46, s[18:19]
	global_load_dwordx4 v[206:209], v[86:87], off
	v_lshlrev_b32_e32 v46, 2, v84
	global_load_dwordx4 v[212:215], v46, s[20:21]
	v_lshlrev_b32_e32 v46, 2, v84
	global_load_dwordx4 v[220:223], v46, s[18:19]
	global_load_dwordx4 v[224:227], v[90:91], off
	v_lshlrev_b32_e32 v46, 2, v88
	global_load_dwordx4 v[228:231], v46, s[20:21]
	v_lshlrev_b32_e32 v46, 2, v88
	global_load_dwordx4 v[238:241], v46, s[18:19]
	global_load_dwordx4 v[242:245], v[94:95], off
	v_lshlrev_b32_e32 v46, 2, v92
	global_load_dwordx4 v[246:249], v46, s[20:21]
	v_lshlrev_b32_e32 v46, 2, v92
	global_load_dwordx4 v[250:253], v46, s[18:19]
	v_cvt_pk_bf16_f32 v46, v62, v63
	v_cvt_pk_bf16_f32 v47, v56, v57
	global_store_dwordx2 v127, v[46:47], s[2:3] offset:2048
	v_cvt_pk_bf16_f32 v46, v52, v53
	v_cvt_pk_bf16_f32 v47, v50, v51
	global_store_dwordx2 v127, v[46:47], s[2:3] offset:2560
	v_cvt_pk_bf16_f32 v46, v44, v45
	v_cvt_pk_bf16_f32 v47, v42, v43
	global_store_dwordx2 v127, v[46:47], s[2:3] offset:3072
	v_cvt_pk_bf16_f32 v46, v36, v37
	v_cvt_pk_bf16_f32 v47, v34, v35
	global_store_dwordx2 v127, v[46:47], s[2:3] offset:3584
	v_lshlrev_b32_e32 v64, 2, v80
	v_lshlrev_b32_e32 v64, 2, v84
	v_lshlrev_b32_e32 v64, 2, v88
	v_lshlrev_b32_e32 v64, 2, v92
	v_lshlrev_b32_e32 v64, 2, v96
	v_lshlrev_b32_e32 v65, 2, v100
	v_lshlrev_b32_e32 v127, 2, v104
	s_waitcnt vmcnt(0)
	v_pk_mul_f32 v[26:27], v[26:27], v[188:189]
	v_pk_mul_f32 v[28:29], v[28:29], v[190:191]
	v_pk_add_f32 v[46:47], v[196:197], 1.0 op_sel_hi:[1,0]
	v_pk_add_f32 v[48:49], v[194:195], 1.0 op_sel_hi:[1,0]
	v_pk_fma_f32 v[46:47], v[28:29], v[46:47], v[204:205]
	v_pk_fma_f32 v[48:49], v[26:27], v[48:49], v[202:203]
	v_pk_mul_f32 v[22:23], v[22:23], v[206:207]
	v_pk_mul_f32 v[24:25], v[24:25], v[208:209]
	v_pk_add_f32 v[26:27], v[214:215], 1.0 op_sel_hi:[1,0]
	v_pk_add_f32 v[28:29], v[212:213], 1.0 op_sel_hi:[1,0]
	v_pk_fma_f32 v[26:27], v[24:25], v[26:27], v[222:223]
	v_pk_fma_f32 v[28:29], v[22:23], v[28:29], v[220:221]
	v_pk_mul_f32 v[18:19], v[18:19], v[224:225]
	v_pk_mul_f32 v[20:21], v[20:21], v[226:227]
	v_pk_add_f32 v[22:23], v[230:231], 1.0 op_sel_hi:[1,0]
	v_pk_add_f32 v[24:25], v[228:229], 1.0 op_sel_hi:[1,0]
	v_pk_fma_f32 v[22:23], v[20:21], v[22:23], v[240:241]
	v_pk_fma_f32 v[24:25], v[18:19], v[24:25], v[238:239]
	v_pk_mul_f32 v[18:19], v[32:33], v[120:121] op_sel_hi:[1,0]
	v_pk_mul_f32 v[20:21], v[30:31], v[120:121] op_sel_hi:[1,0]
	v_pk_mul_f32 v[18:19], v[18:19], v[244:245]
	v_pk_mul_f32 v[20:21], v[20:21], v[242:243]
	v_pk_add_f32 v[30:31], v[248:249], 1.0 op_sel_hi:[1,0]
	v_pk_add_f32 v[32:33], v[246:247], 1.0 op_sel_hi:[1,0]
	v_pk_fma_f32 v[18:19], v[18:19], v[30:31], v[252:253]
	v_pk_fma_f32 v[20:21], v[20:21], v[32:33], v[250:251]
	global_load_dwordx4 v[188:191], v[98:99], off
	global_load_dwordx4 v[194:197], v64, s[20:21]
	global_load_dwordx4 v[202:205], v[102:103], off
	v_cvt_pk_bf16_f32 v30, v48, v49
	v_cvt_pk_bf16_f32 v31, v46, v47
	v_lshlrev_b32_e32 v32, 1, v80
	global_store_dwordx2 v32, v[30:31], s[2:3]
	v_cvt_pk_bf16_f32 v30, v28, v29
	v_cvt_pk_bf16_f32 v31, v26, v27
	v_lshlrev_b32_e32 v32, 1, v84
	global_store_dwordx2 v32, v[30:31], s[2:3]
	v_cvt_pk_bf16_f32 v30, v24, v25
	v_cvt_pk_bf16_f32 v31, v22, v23
	v_lshlrev_b32_e32 v32, 1, v88
	global_store_dwordx2 v32, v[30:31], s[2:3]
	v_cvt_pk_bf16_f32 v30, v20, v21
	v_cvt_pk_bf16_f32 v31, v18, v19
	v_lshlrev_b32_e32 v32, 1, v92
	global_store_dwordx2 v32, v[30:31], s[2:3]
	s_nop 0
	global_load_dwordx4 v[136:139], v65, s[20:21]
	global_load_dwordx4 v[140:143], v[106:107], off
	global_load_dwordx4 v[144:147], v127, s[20:21]
	global_load_dwordx4 v[148:151], v[110:111], off
	global_load_dwordx4 v[152:155], v64, s[18:19]
	global_load_dwordx4 v[156:159], v65, s[18:19]
	global_load_dwordx4 v[160:163], v127, s[18:19]
	v_lshlrev_b32_e32 v64, 2, v108
	global_load_dwordx4 v[164:167], v64, s[20:21]
	global_load_dwordx4 v[170:173], v64, s[18:19]
	v_pk_mul_f32 v[64:65], v[16:17], v[120:121] op_sel_hi:[1,0]
	s_waitcnt vmcnt(0)
	v_pk_mul_f32 v[2:3], v[2:3], v[188:189]
	v_pk_mul_f32 v[4:5], v[4:5], v[190:191]
	v_pk_add_f32 v[16:17], v[196:197], 1.0 op_sel_hi:[1,0]
	v_pk_add_f32 v[30:31], v[194:195], 1.0 op_sel_hi:[1,0]
	v_pk_add_f32 v[32:33], v[138:139], 1.0 op_sel_hi:[1,0]
	v_pk_mul_f32 v[138:139], v[14:15], v[148:149]
	v_pk_fma_f32 v[14:15], v[4:5], v[16:17], v[154:155]
	v_pk_fma_f32 v[16:17], v[2:3], v[30:31], v[152:153]
	v_pk_mul_f32 v[2:3], v[64:65], v[150:151]
	v_pk_add_f32 v[4:5], v[166:167], 1.0 op_sel_hi:[1,0]
	v_pk_add_f32 v[30:31], v[164:165], 1.0 op_sel_hi:[1,0]
	v_pk_fma_f32 v[2:3], v[2:3], v[4:5], v[172:173]
	v_pk_fma_f32 v[4:5], v[138:139], v[30:31], v[170:171]
	v_max_f32_e64 v30, |v116|, |v117|
	v_max_f32_e64 v31, |v60|, |v61|
	v_pk_mul_f32 v[8:9], v[8:9], v[204:205]
	v_max3_f32 v30, |v118|, |v119|, v30
	v_max3_f32 v31, |v114|, |v115|, v31
	v_pk_mul_f32 v[130:131], v[10:11], v[140:141]
	v_pk_fma_f32 v[10:11], v[8:9], v[32:33], v[158:159]
	v_max3_f32 v30, v30, 0, v31
	v_max_f32_e64 v31, |v40|, |v41|
	v_max_f32_e64 v32, |v38|, |v39|
	v_max3_f32 v31, |v58|, |v59|, v31
	v_max3_f32 v32, |v54|, |v55|, v32
	v_max3_f32 v30, v30, v31, v32
	v_max_f32_e64 v31, |v56|, |v57|
	v_max_f32_e64 v32, |v50|, |v51|
	v_max3_f32 v31, |v62|, |v63|, v31
	v_max3_f32 v32, |v52|, |v53|, v32
	v_max3_f32 v30, v30, v31, v32
	v_max_f32_e64 v31, |v42|, |v43|
	v_max_f32_e64 v32, |v34|, |v35|
	v_max3_f32 v31, |v44|, |v45|, v31
	v_max3_f32 v32, |v36|, |v37|, v32
	v_max3_f32 v30, v30, v31, v32
	v_max_f32_e64 v31, |v46|, |v47|
	v_max_f32_e64 v32, |v26|, |v27|
	v_max3_f32 v31, |v48|, |v49|, v31
	v_max3_f32 v32, |v28|, |v29|, v32
	v_max3_f32 v30, v30, v31, v32
	v_max_f32_e64 v31, |v22|, |v23|
	v_max_f32_e64 v32, |v18|, |v19|
	v_pk_mul_f32 v[6:7], v[6:7], v[202:203]
	v_pk_add_f32 v[128:129], v[136:137], 1.0 op_sel_hi:[1,0]
	v_max3_f32 v31, |v24|, |v25|, v31
	v_max3_f32 v32, |v20|, |v21|, v32
	v_pk_mul_f32 v[132:133], v[12:13], v[142:143]
	v_pk_add_f32 v[134:135], v[146:147], 1.0 op_sel_hi:[1,0]
	v_pk_fma_f32 v[12:13], v[6:7], v[128:129], v[156:157]
	v_max3_f32 v30, v30, v31, v32
	v_max_f32_e64 v31, |v14|, |v15|
	v_max_f32_e64 v32, |v10|, |v11|
	v_pk_add_f32 v[136:137], v[144:145], 1.0 op_sel_hi:[1,0]
	v_pk_fma_f32 v[6:7], v[132:133], v[134:135], v[162:163]
	v_max3_f32 v31, |v16|, |v17|, v31
	v_max3_f32 v32, |v12|, |v13|, v32
	v_pk_fma_f32 v[8:9], v[130:131], v[136:137], v[160:161]
	v_max3_f32 v30, v30, v31, v32
	v_max_f32_e64 v31, |v6|, |v7|
	v_max_f32_e64 v32, |v2|, |v3|
	v_max3_f32 v31, |v8|, |v9|, v31
	v_max3_f32 v32, |v4|, |v5|, v32
	v_max3_f32 v30, v30, v31, v32
	ds_bpermute_b32 v31, v1, v30
	v_lshlrev_b32_e32 v64, 1, v96
	s_waitcnt lgkmcnt(0)
	v_max_f32_e32 v31, v31, v31
	v_max_f32_e32 v30, v30, v31
	ds_bpermute_b32 v31, v81, v30
	s_waitcnt lgkmcnt(0)
	v_max_f32_e32 v31, v31, v31
	v_max_f32_e32 v32, v30, v31
	ds_bpermute_b32 v33, v85, v32
	v_cvt_pk_bf16_f32 v30, v16, v17
	v_cvt_pk_bf16_f32 v31, v14, v15
	global_store_dwordx2 v64, v[30:31], s[2:3]
	v_cvt_pk_bf16_f32 v31, v10, v11
	s_waitcnt lgkmcnt(0)
	v_max_f32_e32 v30, v33, v33
	v_max_f32_e32 v32, v32, v30
	ds_bpermute_b32 v33, v89, v32
	v_cvt_pk_bf16_f32 v30, v12, v13
	v_lshlrev_b32_e32 v64, 1, v100
	global_store_dwordx2 v64, v[30:31], s[2:3]
	v_cvt_pk_bf16_f32 v31, v6, v7
	s_waitcnt lgkmcnt(0)
	v_max_f32_e32 v30, v33, v33
	v_max_f32_e32 v32, v32, v30
	ds_bpermute_b32 v33, v93, v32
	v_cvt_pk_bf16_f32 v30, v8, v9
	v_lshlrev_b32_e32 v64, 1, v104
	global_store_dwordx2 v64, v[30:31], s[2:3]
	v_cvt_pk_bf16_f32 v31, v2, v3
	s_waitcnt lgkmcnt(0)
	v_max_f32_e32 v30, v33, v33
	v_max_f32_e32 v32, v32, v30
	ds_bpermute_b32 v33, v97, v32
	v_cvt_pk_bf16_f32 v30, v4, v5
	v_lshlrev_b32_e32 v64, 1, v108
	global_store_dwordx2 v64, v[30:31], s[2:3]
	s_waitcnt lgkmcnt(0)
	v_max_f32_e32 v30, v33, v33
	v_max_f32_e32 v30, v32, v30
	s_and_saveexec_b64 s[2:3], s[0:1]
	s_cbranch_execz .LBB0_264
	s_lshl_b64 s[18:19], s[16:17], 2
	s_add_u32 s18, s24, s18
	v_mul_f32_e32 v31, 0x3c010204, v30
	s_addc_u32 s19, s25, s19
	global_store_dword v67, v31, s[18:19]
	s_branch .LBB0_264
